# attention: s_setprio 1 for waves 4-7 from S1 start until after PV MFMA 8, on top of hand-scheduled S2
# speedup vs baseline: 1.0148x; 1.0148x over previous
; #define LOADV(dst, ks_) do { _Pragma("unroll") for (int dvb = 0; dvb < 4; ++dvb) { dst[2 * dvb] = vtr(vp + dvb * 4096 + (ks_) * 1024); dst[2 * dvb + 1] = vtr(vp + dvb * 4096 + (ks_) * 1024 + 512); } } while (0)
; #define MF4(src, pfrag) do { _Pragma("unroll") for (int dvb = 0; dvb < 4; ++dvb) { \
;         const bf16x8 vf_ = __builtin_shufflevector(src[2 * dvb], src[2 * dvb + 1], 0, 1, 2, 3, 4, 5, 6, 7); o[dvb] = MFMA32(vf_, pfrag, o[dvb]); } } while (0)
; #define EXPQ(S, lo_, RS, PF) do { _Pragma("unroll") for (int i = lo_; i < lo_ + 8; ++i) { S[i] = ex2(S[i]); RS += S[i]; } \
;               u32x4 w_; w_.x = pk2(S[lo_], S[lo_ + 1]); w_.y = pk2(S[lo_ + 2], S[lo_ + 3]); w_.z = pk2(S[lo_ + 4], S[lo_ + 5]); w_.w = pk2(S[lo_ + 6], S[lo_ + 7]); PF = __builtin_bit_cast(bf16x8, w_); } while (0)
; DI void attn_unit(const Params& p, int bh, int qb, char* lds, float lam, int tid, int lane, int wid, const bool build_tab) {
;     ...
;             float rs0 = 0.f, rs1 = 0.f;
;     ...
;             EXPQ(s0, 0, rs0, pf[0]);
;             LOADV(vb, 1);
;             MF4(va, pf[0]);
;             EXPQ(s0, 8, rs1, pf[1]);
;             LOADV(va, 2);
;             MF4(vb, pf[1]);
;             EXPQ(s1, 0, rs0, pf[2]);
;             LOADV(vb, 3);
;             MF4(va, pf[2]);
;             EXPQ(s1, 8, rs1, pf[3]);
;             MF4(vb, pf[3]);
;             l += rs0 + rs1;
.LBB0_359:
	ds_read_b64_tr_b16 v[242:243], v220 offset:21504
	ds_read_b64_tr_b16 v[244:245], v220 offset:22016
	ds_read_b64_tr_b16 v[246:247], v220 offset:25600
	ds_read_b64_tr_b16 v[248:249], v220 offset:26112
	v_exp_f32_e32 v222, v96
	v_exp_f32_e32 v224, v97
	v_exp_f32_e32 v226, v98
	v_exp_f32_e32 v228, v99
	v_exp_f32_e32 v230, v100
	v_exp_f32_e32 v232, v101
	v_exp_f32_e32 v234, v102
	v_exp_f32_e32 v236, v103
	v_cvt_pk_bf16_f32 v96, v222, v224
	v_cvt_pk_bf16_f32 v97, v226, v228
	v_cvt_pk_bf16_f32 v98, v230, v232
	v_cvt_pk_bf16_f32 v99, v234, v236
	ds_read_b64_tr_b16 v[100:101], v220 offset:17408
	ds_read_b64_tr_b16 v[102:103], v220 offset:17920
	s_waitcnt lgkmcnt(12)
	v_mfma_f32_32x32x16_bf16 v[48:63], v[140:143], v[96:99], v[48:63]
	ds_read_b64_tr_b16 v[250:251], v220 offset:29696
	ds_read_b64_tr_b16 v[252:253], v220 offset:30208
	v_exp_f32_e32 v223, v104
	v_exp_f32_e32 v225, v105
	v_exp_f32_e32 v227, v106
	v_add_f32_e32 v221, v224, v222
	s_waitcnt lgkmcnt(12)
	v_mfma_f32_32x32x16_bf16 v[32:47], v[136:139], v[96:99], v[32:47]
	v_exp_f32_e32 v229, v107
	v_exp_f32_e32 v231, v108
	v_exp_f32_e32 v233, v109
	v_add_f32_e32 v221, v226, v221
	s_waitcnt lgkmcnt(10)
	v_mfma_f32_32x32x16_bf16 v[16:31], v[132:135], v[96:99], v[16:31]
	v_exp_f32_e32 v235, v110
	v_exp_f32_e32 v237, v111
	v_add_f32_e32 v221, v228, v221
	v_add_f32_e32 v221, v230, v221
	ds_read_b64_tr_b16 v[104:105], v220 offset:18432
	ds_read_b64_tr_b16 v[106:107], v220 offset:18944
	ds_read_b64_tr_b16 v[108:109], v220 offset:19456
	ds_read_b64_tr_b16 v[110:111], v220 offset:19968
	s_waitcnt lgkmcnt(12)
	v_mfma_f32_32x32x16_bf16 v[0:15], v[128:131], v[96:99], v[0:15]
	ds_read_b64_tr_b16 v[128:129], v220 offset:26624
	ds_read_b64_tr_b16 v[130:131], v220 offset:27136
	v_cvt_pk_bf16_f32 v96, v223, v225
	v_cvt_pk_bf16_f32 v97, v227, v229
	v_cvt_pk_bf16_f32 v98, v231, v233
	v_cvt_pk_bf16_f32 v99, v235, v237
	v_exp_f32_e32 v140, v84
	v_exp_f32_e32 v142, v85
	s_waitcnt lgkmcnt(8)
	v_mfma_f32_32x32x16_bf16 v[48:63], v[100:103], v[96:99], v[48:63]
	v_exp_f32_e32 v238, v86
	v_exp_f32_e32 v240, v87
	v_add_f32_e32 v221, v232, v221
	ds_read_b64_tr_b16 v[84:85], v220 offset:22528
	ds_read_b64_tr_b16 v[86:87], v220 offset:23040
	v_exp_f32_e32 v136, v82
	s_waitcnt lgkmcnt(14)
	v_mfma_f32_32x32x16_bf16 v[32:47], v[242:245], v[96:99], v[32:47]
	ds_read_b64_tr_b16 v[242:243], v220 offset:23552
	ds_read_b64_tr_b16 v[244:245], v220 offset:24064
	v_exp_f32_e32 v138, v83
	v_exp_f32_e32 v132, v80
	v_exp_f32_e32 v134, v81
	v_add_f32_e32 v221, v234, v221
	s_waitcnt lgkmcnt(14)
	v_mfma_f32_32x32x16_bf16 v[16:31], v[246:249], v[96:99], v[16:31]
	ds_read_b64_tr_b16 v[246:247], v220 offset:27648
	ds_read_b64_tr_b16 v[248:249], v220 offset:28160
	v_cvt_pk_bf16_f32 v80, v132, v134
	v_cvt_pk_bf16_f32 v81, v136, v138
	v_cvt_pk_bf16_f32 v82, v140, v142
	v_cvt_pk_bf16_f32 v83, v238, v240
	v_exp_f32_e32 v133, v88
	v_exp_f32_e32 v135, v89
	s_waitcnt lgkmcnt(12)
	v_mfma_f32_32x32x16_bf16 v[0:15], v[250:253], v[96:99], v[0:15]
	s_setprio 0
	ds_read_b64_tr_b16 v[250:251], v220 offset:31744
	ds_read_b64_tr_b16 v[252:253], v220 offset:32256
	v_exp_f32_e32 v137, v90
	v_exp_f32_e32 v139, v91
	v_add_f32_e32 v221, v236, v221
	ds_read_b64_tr_b16 v[88:89], v220 offset:30720
	ds_read_b64_tr_b16 v[90:91], v220 offset:31232
	v_exp_f32_e32 v141, v92
	s_waitcnt lgkmcnt(14)
	v_mfma_f32_32x32x16_bf16 v[48:63], v[104:107], v[80:83], v[48:63]
	v_exp_f32_e32 v143, v93
	v_exp_f32_e32 v239, v94
	v_exp_f32_e32 v241, v95
	v_add_f32_e32 v221, v132, v221
	s_waitcnt lgkmcnt(8)
	v_mfma_f32_32x32x16_bf16 v[32:47], v[84:87], v[80:83], v[32:47]
	v_add_f32_e32 v93, v225, v223
	v_add_f32_e32 v221, v134, v221
	v_add_f32_e32 v93, v227, v93
	v_add_f32_e32 v221, v136, v221
	v_add_f32_e32 v93, v229, v93
	v_add_f32_e32 v221, v138, v221
	s_waitcnt lgkmcnt(10)
	v_mfma_f32_32x32x16_bf16 v[16:31], v[128:131], v[80:83], v[16:31]
	v_add_f32_e32 v93, v231, v93
	v_add_f32_e32 v221, v140, v221
	v_add_f32_e32 v93, v233, v93
	v_add_f32_e32 v221, v142, v221
	v_add_f32_e32 v93, v235, v93
	v_add_f32_e32 v221, v238, v221
	v_add_f32_e32 v93, v237, v93
	s_waitcnt lgkmcnt(0)
	v_mfma_f32_32x32x16_bf16 v[0:15], v[88:91], v[80:83], v[0:15]
	v_cvt_pk_bf16_f32 v80, v133, v135
	v_cvt_pk_bf16_f32 v81, v137, v139
	v_cvt_pk_bf16_f32 v82, v141, v143
	v_cvt_pk_bf16_f32 v83, v239, v241
	v_add_f32_e32 v221, v240, v221
	v_add_f32_e32 v93, v133, v93
	s_waitcnt lgkmcnt(12)
	v_mfma_f32_32x32x16_bf16 v[48:63], v[108:111], v[80:83], v[48:63]
	v_add_f32_e32 v93, v135, v93
	v_add_f32_e32 v93, v137, v93
	s_waitcnt lgkmcnt(6)
	v_mfma_f32_32x32x16_bf16 v[32:47], v[242:245], v[80:83], v[32:47]
	v_add_f32_e32 v93, v139, v93
	v_add_f32_e32 v93, v141, v93
	s_waitcnt lgkmcnt(4)
	v_mfma_f32_32x32x16_bf16 v[16:31], v[246:249], v[80:83], v[16:31]
	v_add_f32_e32 v93, v143, v93
	v_add_f32_e32 v93, v239, v93
	s_waitcnt lgkmcnt(2)
	v_mfma_f32_32x32x16_bf16 v[0:15], v[250:253], v[80:83], v[0:15]
	v_add_f32_e32 v93, v241, v93
	v_add_f32_e32 v221, v221, v93
	v_add_f32_e32 v146, v146, v221

; #define LOADV(dst, ks_) do { _Pragma("unroll") for (int dvb = 0; dvb < 4; ++dvb) { dst[2 * dvb] = vtr(vp + dvb * 4096 + (ks_) * 1024); dst[2 * dvb + 1] = vtr(vp + dvb * 4096 + (ks_) * 1024 + 512); } } while (0)
; #define MF4(src, pfrag) do { _Pragma("unroll") for (int dvb = 0; dvb < 4; ++dvb) { \
;         const bf16x8 vf_ = __builtin_shufflevector(src[2 * dvb], src[2 * dvb + 1], 0, 1, 2, 3, 4, 5, 6, 7); o[dvb] = MFMA32(vf_, pfrag, o[dvb]); } } while (0)
; #define EXPQ(S, lo_, RS, PF) do { _Pragma("unroll") for (int i = lo_; i < lo_ + 8; ++i) { S[i] = ex2(S[i]); RS += S[i]; } \
;               u32x4 w_; w_.x = pk2(S[lo_], S[lo_ + 1]); w_.y = pk2(S[lo_ + 2], S[lo_ + 3]); w_.z = pk2(S[lo_ + 4], S[lo_ + 5]); w_.w = pk2(S[lo_ + 6], S[lo_ + 7]); PF = __builtin_bit_cast(bf16x8, w_); } while (0)
; DI void attn_unit(const Params& p, int bh, int qb, char* lds, float lam, int tid, int lane, int wid, const bool build_tab) {
;     ...
;             float rs0 = 0.f, rs1 = 0.f;
;     ...
;             EXPQ(s0, 0, rs0, pf[0]);
;             LOADV(vb, 1);
;             MF4(va, pf[0]);
;             EXPQ(s0, 8, rs1, pf[1]);
;             LOADV(va, 2);
;             MF4(vb, pf[1]);
;             EXPQ(s1, 0, rs0, pf[2]);
;             LOADV(vb, 3);
;             MF4(va, pf[2]);
;             EXPQ(s1, 8, rs1, pf[3]);
;             MF4(vb, pf[3]);
;             l += rs0 + rs1;
.LBB0_379:
	ds_read_b64_tr_b16 v[230:231], v177 offset:21504
	ds_read_b64_tr_b16 v[232:233], v177 offset:22016
	ds_read_b64_tr_b16 v[234:235], v177 offset:25600
	ds_read_b64_tr_b16 v[236:237], v177 offset:26112
	v_exp_f32_e32 v178, v96
	v_exp_f32_e32 v180, v97
	v_exp_f32_e32 v182, v98
	v_exp_f32_e32 v184, v99
	v_exp_f32_e32 v186, v100
	v_exp_f32_e32 v188, v101
	v_exp_f32_e32 v190, v102
	v_exp_f32_e32 v192, v103
	v_cvt_pk_bf16_f32 v96, v178, v180
	v_cvt_pk_bf16_f32 v97, v182, v184
	v_cvt_pk_bf16_f32 v98, v186, v188
	v_cvt_pk_bf16_f32 v99, v190, v192
	ds_read_b64_tr_b16 v[100:101], v177 offset:17408
	ds_read_b64_tr_b16 v[102:103], v177 offset:17920
	s_waitcnt lgkmcnt(12)
	v_mfma_f32_32x32x16_bf16 v[48:63], v[140:143], v[96:99], v[48:63]
	ds_read_b64_tr_b16 v[238:239], v177 offset:29696
	ds_read_b64_tr_b16 v[240:241], v177 offset:30208
	v_exp_f32_e32 v179, v104
	v_exp_f32_e32 v181, v105
	v_exp_f32_e32 v183, v106
	v_add_f32_e32 v242, v180, v178
	s_waitcnt lgkmcnt(12)
	v_mfma_f32_32x32x16_bf16 v[32:47], v[136:139], v[96:99], v[32:47]
	v_exp_f32_e32 v185, v107
	v_exp_f32_e32 v187, v108
	v_exp_f32_e32 v189, v109
	v_add_f32_e32 v242, v182, v242
	s_waitcnt lgkmcnt(10)
	v_mfma_f32_32x32x16_bf16 v[16:31], v[132:135], v[96:99], v[16:31]
	v_exp_f32_e32 v191, v110
	v_exp_f32_e32 v193, v111
	v_add_f32_e32 v242, v184, v242
	v_add_f32_e32 v242, v186, v242
	ds_read_b64_tr_b16 v[104:105], v177 offset:18432
	ds_read_b64_tr_b16 v[106:107], v177 offset:18944
	ds_read_b64_tr_b16 v[108:109], v177 offset:19456
	ds_read_b64_tr_b16 v[110:111], v177 offset:19968
	s_waitcnt lgkmcnt(12)
	v_mfma_f32_32x32x16_bf16 v[0:15], v[128:131], v[96:99], v[0:15]
	ds_read_b64_tr_b16 v[128:129], v177 offset:26624
	ds_read_b64_tr_b16 v[130:131], v177 offset:27136
	v_cvt_pk_bf16_f32 v96, v179, v181
	v_cvt_pk_bf16_f32 v97, v183, v185
	v_cvt_pk_bf16_f32 v98, v187, v189
	v_cvt_pk_bf16_f32 v99, v191, v193
	v_exp_f32_e32 v140, v84
	v_exp_f32_e32 v142, v85
	s_waitcnt lgkmcnt(8)
	v_mfma_f32_32x32x16_bf16 v[48:63], v[100:103], v[96:99], v[48:63]
	v_exp_f32_e32 v194, v86
	v_exp_f32_e32 v196, v87
	v_add_f32_e32 v242, v188, v242
	ds_read_b64_tr_b16 v[84:85], v177 offset:22528
	ds_read_b64_tr_b16 v[86:87], v177 offset:23040
	v_exp_f32_e32 v136, v82
	s_waitcnt lgkmcnt(14)
	v_mfma_f32_32x32x16_bf16 v[32:47], v[230:233], v[96:99], v[32:47]
	ds_read_b64_tr_b16 v[230:231], v177 offset:23552
	ds_read_b64_tr_b16 v[232:233], v177 offset:24064
	v_exp_f32_e32 v138, v83
	v_exp_f32_e32 v132, v80
	v_exp_f32_e32 v134, v81
	v_add_f32_e32 v242, v190, v242
	s_waitcnt lgkmcnt(14)
	v_mfma_f32_32x32x16_bf16 v[16:31], v[234:237], v[96:99], v[16:31]
	ds_read_b64_tr_b16 v[234:235], v177 offset:27648
	ds_read_b64_tr_b16 v[236:237], v177 offset:28160
	v_cvt_pk_bf16_f32 v80, v132, v134
	v_cvt_pk_bf16_f32 v81, v136, v138
	v_cvt_pk_bf16_f32 v82, v140, v142
	v_cvt_pk_bf16_f32 v83, v194, v196
	v_exp_f32_e32 v133, v88
	v_exp_f32_e32 v135, v89
	s_waitcnt lgkmcnt(12)
	v_mfma_f32_32x32x16_bf16 v[0:15], v[238:241], v[96:99], v[0:15]
	s_setprio 0
	ds_read_b64_tr_b16 v[238:239], v177 offset:31744
	ds_read_b64_tr_b16 v[240:241], v177 offset:32256
	v_exp_f32_e32 v137, v90
	v_exp_f32_e32 v139, v91
	v_add_f32_e32 v242, v192, v242
	ds_read_b64_tr_b16 v[88:89], v177 offset:30720
	ds_read_b64_tr_b16 v[90:91], v177 offset:31232
	v_exp_f32_e32 v141, v92
	s_waitcnt lgkmcnt(14)
	v_mfma_f32_32x32x16_bf16 v[48:63], v[104:107], v[80:83], v[48:63]
	v_exp_f32_e32 v143, v93
	v_exp_f32_e32 v195, v94
	v_exp_f32_e32 v197, v95
	v_add_f32_e32 v242, v132, v242
	s_waitcnt lgkmcnt(8)
	v_mfma_f32_32x32x16_bf16 v[32:47], v[84:87], v[80:83], v[32:47]
	v_add_f32_e32 v243, v181, v179
	v_add_f32_e32 v242, v134, v242
	v_add_f32_e32 v243, v183, v243
	v_add_f32_e32 v242, v136, v242
	v_add_f32_e32 v243, v185, v243
	v_add_f32_e32 v242, v138, v242
	s_waitcnt lgkmcnt(10)
	v_mfma_f32_32x32x16_bf16 v[16:31], v[128:131], v[80:83], v[16:31]
	v_add_f32_e32 v243, v187, v243
	v_add_f32_e32 v242, v140, v242
	v_add_f32_e32 v243, v189, v243
	v_add_f32_e32 v242, v142, v242
	v_add_f32_e32 v243, v191, v243
	v_add_f32_e32 v242, v194, v242
	v_add_f32_e32 v243, v193, v243
	s_waitcnt lgkmcnt(0)
	v_mfma_f32_32x32x16_bf16 v[0:15], v[88:91], v[80:83], v[0:15]
	v_cvt_pk_bf16_f32 v80, v133, v135
	v_cvt_pk_bf16_f32 v81, v137, v139
	v_cvt_pk_bf16_f32 v82, v141, v143
	v_cvt_pk_bf16_f32 v83, v195, v197
	v_add_f32_e32 v242, v196, v242
	v_add_f32_e32 v243, v133, v243
	s_waitcnt lgkmcnt(12)
	v_mfma_f32_32x32x16_bf16 v[48:63], v[108:111], v[80:83], v[48:63]
	v_add_f32_e32 v243, v135, v243
	v_add_f32_e32 v243, v137, v243
	s_waitcnt lgkmcnt(6)
	v_mfma_f32_32x32x16_bf16 v[32:47], v[230:233], v[80:83], v[32:47]
	v_add_f32_e32 v243, v139, v243
	v_add_f32_e32 v243, v141, v243
	s_waitcnt lgkmcnt(4)
	v_mfma_f32_32x32x16_bf16 v[16:31], v[234:237], v[80:83], v[16:31]
	v_add_f32_e32 v243, v143, v243
	v_add_f32_e32 v243, v195, v243
	s_waitcnt lgkmcnt(2)
	v_mfma_f32_32x32x16_bf16 v[0:15], v[238:241], v[80:83], v[0:15]
	v_add_f32_e32 v243, v197, v243
	v_add_f32_e32 v242, v242, v243
	v_add_f32_e32 v176, v176, v242
